# P5 (post-norm + residual): the f32 residual-stream stores to d_out marked non-temporal so the 134 MB stream does not displace the bf16 activations the next GEMM re-reads
# speedup vs baseline: 1.0107x; 1.0107x over previous
; __device__ __forceinline__ void p5_row2(const Args& a, int rowA, int rowB, int lane) {
;     const float* SSQ = (const float*)(a.ws + WS_SSQ);
;     float sa = lane < 32 ? SSQ[(size_t)rowA * 32 + lane] : 0.f, sb = lane < 32 ? SSQ[(size_t)rowB * 32 + lane] : 0.f;
;     const v2u* mbA = (const v2u*)((const bf16*)(a.ws + WS_MB) + (size_t)rowA * 2048) + lane; const v2u* mbB = (const v2u*)((const bf16*)(a.ws + WS_MB) + (size_t)rowB * 2048) + lane;
;     const f32x4* xA = (const f32x4*)(a.in[0] + (size_t)rowA * 2048) + lane; const f32x4* xB = (const f32x4*)(a.in[0] + (size_t)rowB * 2048) + lane;
;     const f32x4* g1 = (const f32x4*)a.in[22] + lane; const f32x4* g2 = (const f32x4*)a.in[23] + lane;
;     f32x4 v[8], w[8]; v2u ma[8], mb_[8];
; #pragma unroll
;     for (int jj = 0; jj < 8; ++jj) { v[jj] = xA[64 * jj]; w[jj] = xB[64 * jj]; ma[jj] = mbA[64 * jj]; mb_[jj] = mbB[64 * jj]; }
; #pragma unroll
;     for (int o = 1; o < 64; o <<= 1) { sa += __shfl_xor(sa, o); sb += __shfl_xor(sb, o); }
;     const float ra = 1.f / sqrtf(sa * (1.f / DMODEL) + RMS_EPS), rb = 1.f / sqrtf(sb * (1.f / DMODEL) + RMS_EPS);
.LBB0_790:
	s_or_b64 exec, exec, s[4:5]
	s_waitcnt vmcnt(0)
	ds_bpermute_b32 v10, v200, v2
	s_add_u32 s4, s90, s12
	v_lshlrev_b64 v[78:79], 3, v[0:1]
	s_addc_u32 s5, s91, s13
	s_lshl_b64 s[26:27], s[2:3], 12
	v_lshl_add_u64 v[76:77], s[4:5], 0, v[78:79]
	s_add_u32 s4, s70, s26
	s_addc_u32 s5, s71, s27
	v_lshl_add_u64 v[86:87], s[4:5], 0, v[78:79]
	s_add_u32 s4, s24, s16
	s_waitcnt lgkmcnt(0)
	v_add_f32_e32 v2, v2, v10
	s_addc_u32 s5, s25, s17
	s_lshl_b64 s[28:29], s[2:3], 13
	ds_bpermute_b32 v10, v201, v2
	v_lshlrev_b64 v[80:81], 4, v[0:1]
	s_add_u32 s2, s68, s28
	v_add_co_u32_e32 v82, vcc, s11, v76
	v_lshl_add_u64 v[0:1], s[4:5], 0, v[80:81]
	s_addc_u32 s3, s69, s29
	v_addc_co_u32_e32 v83, vcc, 0, v77, vcc
	v_lshl_add_u64 v[8:9], s[2:3], 0, v[80:81]
	global_load_dwordx4 v[12:15], v[0:1], off
	global_load_dwordx4 v[20:23], v[0:1], off offset:1024
	global_load_dwordx4 v[4:7], v[8:9], off
	global_load_dwordx4 v[16:19], v[8:9], off offset:1024
	global_load_dwordx4 v[48:51], v[0:1], off offset:2048
	global_load_dwordx4 v[56:59], v[0:1], off offset:3072
	global_load_dwordx4 v[60:63], v[8:9], off offset:2048
	global_load_dwordx4 v[44:47], v[8:9], off offset:3072
	global_load_dwordx2 v[114:115], v[82:83], off
	global_load_dwordx2 v[110:111], v[82:83], off offset:512
	global_load_dwordx2 v[104:105], v[82:83], off offset:1024
	global_load_dwordx2 v[66:67], v[82:83], off offset:1536
	global_load_dwordx2 v[112:113], v[86:87], off
	global_load_dwordx2 v[106:107], v[86:87], off offset:512
	global_load_dwordx2 v[100:101], v[86:87], off offset:1024
	global_load_dwordx2 v[64:65], v[86:87], off offset:1536
	v_add_co_u32_e32 v0, vcc, s30, v0
	s_waitcnt lgkmcnt(0)
	v_add_f32_e32 v2, v2, v10
	v_addc_co_u32_e32 v1, vcc, 0, v1, vcc
	v_add_co_u32_e32 v84, vcc, s30, v8
	ds_bpermute_b32 v8, v200, v3
	s_nop 0
	v_addc_co_u32_e32 v85, vcc, 0, v9, vcc
	ds_bpermute_b32 v9, v202, v2
	v_lshl_add_u64 v[108:109], s[72:73], 0, v[80:81]
	s_waitcnt lgkmcnt(1)
	v_add_f32_e32 v3, v3, v8
	ds_bpermute_b32 v8, v201, v3
	global_load_dwordx4 v[52:55], v[0:1], off
	global_load_dwordx4 v[32:35], v[0:1], off offset:1024
	s_waitcnt lgkmcnt(1)
	v_add_f32_e32 v2, v2, v9
	ds_bpermute_b32 v9, v203, v2
	global_load_dwordx4 v[40:43], v[84:85], off
	global_load_dwordx4 v[36:39], v[84:85], off offset:1024
	s_waitcnt lgkmcnt(1)
	v_add_f32_e32 v3, v3, v8
	ds_bpermute_b32 v28, v202, v3
	v_lshl_add_u64 v[74:75], v[74:75], 0, s[20:21]
	s_waitcnt lgkmcnt(1)
	v_add_f32_e32 v2, v2, v9
	ds_bpermute_b32 v29, v204, v2
	global_load_dwordx4 v[24:27], v[0:1], off offset:2048
	global_load_dwordx4 v[8:11], v[0:1], off offset:3072
	s_waitcnt lgkmcnt(1)
	v_add_f32_e32 v88, v3, v28
	ds_bpermute_b32 v89, v203, v88
	s_waitcnt lgkmcnt(1)
	v_add_f32_e32 v90, v2, v29
	global_load_dwordx4 v[28:31], v[84:85], off offset:2048
	global_load_dwordx4 v[0:3], v[84:85], off offset:3072
	global_load_dwordx4 v[116:119], v[108:109], off
	ds_bpermute_b32 v91, v205, v90
	s_waitcnt lgkmcnt(1)
	v_add_f32_e32 v92, v88, v89
	ds_bpermute_b32 v94, v204, v92
	s_waitcnt lgkmcnt(1)
	v_add_f32_e32 v84, v90, v91
	v_fmamk_f32 v84, v84, 0x3a000000, v93
	v_mul_f32_e32 v85, 0x4f800000, v84
	v_cmp_gt_f32_e32 vcc, s31, v84
	s_waitcnt lgkmcnt(0)
	v_add_f32_e32 v92, v92, v94
	ds_bpermute_b32 v102, v205, v92
	v_cndmask_b32_e32 v90, v84, v85, vcc
	v_sqrt_f32_e32 v91, v90
	global_load_dwordx2 v[96:97], v[82:83], off offset:2048
	global_load_dwordx2 v[88:89], v[82:83], off offset:2560
	global_load_dwordx2 v[84:85], v[82:83], off offset:3072
	s_nop 0
	global_load_dwordx2 v[82:83], v[82:83], off offset:3584
	s_waitcnt lgkmcnt(0)
	v_add_f32_e32 v92, v92, v102
	v_add_u32_e32 v94, -1, v91
	v_fma_f32 v95, -v94, v91, v90
	v_cmp_ge_f32_e64 s[4:5], 0, v95
	v_add_u32_e32 v95, 1, v91
	v_fmamk_f32 v92, v92, 0x3a000000, v93
	v_cndmask_b32_e64 v94, v91, v94, s[4:5]
	v_fma_f32 v91, -v95, v91, v90
	v_cmp_lt_f32_e64 s[4:5], 0, v91
	v_mul_f32_e32 v128, 0x4f800000, v92
	global_load_dwordx4 v[120:123], v[108:109], off offset:1024
	v_cndmask_b32_e64 v91, v94, v95, s[4:5]
	v_mul_f32_e32 v94, 0x37800000, v91
	v_cndmask_b32_e32 v91, v91, v94, vcc
	v_cmp_class_f32_e32 vcc, v90, v103
	v_cmp_gt_f32_e64 s[4:5], s31, v92
	s_nop 0
	v_cndmask_b32_e32 v124, v91, v90, vcc
	v_div_scale_f32 v125, s[2:3], v124, v124, 1.0
	v_rcp_f32_e32 v126, v125
	v_cndmask_b32_e64 v92, v92, v128, s[4:5]
	v_sqrt_f32_e32 v128, v92
	global_load_dwordx2 v[98:99], v[86:87], off offset:2048
	global_load_dwordx2 v[94:95], v[86:87], off offset:2560
	global_load_dwordx2 v[90:91], v[86:87], off offset:3072
	s_nop 0
	global_load_dwordx2 v[86:87], v[86:87], off offset:3584
	v_fma_f32 v102, -v125, v126, 1.0
	v_fmac_f32_e32 v126, v102, v126
	v_div_scale_f32 v102, vcc, 1.0, v124, 1.0
	v_mul_f32_e32 v127, v102, v126
	v_fma_f32 v129, -v125, v127, v102
	v_fmac_f32_e32 v127, v129, v126
	v_fma_f32 v102, -v125, v127, v102
	v_add_u32_e32 v125, -1, v128
	v_fma_f32 v129, -v125, v128, v92
	v_cmp_ge_f32_e64 s[8:9], 0, v129
	v_add_u32_e32 v129, 1, v128
	s_nop 0
	v_cndmask_b32_e64 v125, v128, v125, s[8:9]
	v_fma_f32 v128, -v129, v128, v92
	v_cmp_lt_f32_e64 s[8:9], 0, v128
	s_nop 1
	v_cndmask_b32_e64 v125, v125, v129, s[8:9]
	v_mul_f32_e32 v128, 0x37800000, v125
	v_cndmask_b32_e64 v125, v125, v128, s[4:5]
	v_cmp_class_f32_e64 s[4:5], v92, v103
	s_nop 1
	v_cndmask_b32_e64 v128, v125, v92, s[4:5]
	v_div_scale_f32 v129, s[2:3], v128, v128, 1.0
	v_rcp_f32_e32 v130, v129
	v_div_fmas_f32 v92, v102, v126, v127
	v_div_fixup_f32 v92, v92, v124, 1.0
	global_load_dwordx4 v[124:127], v[108:109], off offset:2048
	v_fma_f32 v102, -v129, v130, 1.0
	v_fmac_f32_e32 v130, v102, v130
	v_div_scale_f32 v102, vcc, 1.0, v128, 1.0
	v_mul_f32_e32 v131, v102, v130
	v_fma_f32 v132, -v129, v131, v102
	v_fmac_f32_e32 v131, v132, v130
	v_fma_f32 v102, -v129, v131, v102
	v_div_fmas_f32 v102, v102, v130, v131
	v_div_fixup_f32 v102, v102, v128, 1.0
	s_waitcnt vmcnt(26)
; __device__ __forceinline__ f32x4 bf4(v2u u) { return (f32x4){bflo(u.x), bfhi(u.x), bflo(u.y), bfhi(u.y)}; }
; __device__ __forceinline__ void p5_row2(const Args& a, int rowA, int rowB, int lane) {
;     ...
; #pragma unroll
;     for (int jj = 0; jj < 8; ++jj) { const f32x4 gg = g1[64 * jj]; v[jj] = v[jj] + bf4(ma[jj]) * ra * gg; w[jj] = w[jj] + bf4(mb_[jj]) * rb * gg;
;         s += (v[jj].x * v[jj].x + v[jj].y * v[jj].y) + (v[jj].z * v[jj].z + v[jj].w * v[jj].w); t += (w[jj].x * w[jj].x + w[jj].y * w[jj].y) + (w[jj].z * w[jj].z + w[jj].w * w[jj].w); }
	v_lshlrev_b32_e32 v128, 16, v114
	v_and_b32_e32 v129, 0xffff0000, v114
	v_lshlrev_b32_e32 v114, 16, v115
	v_and_b32_e32 v115, 0xffff0000, v115
	v_pk_mul_f32 v[114:115], v[92:93], v[114:115] op_sel_hi:[0,1]
	s_waitcnt vmcnt(10)
	v_pk_fma_f32 v[14:15], v[118:119], v[114:115], v[14:15]
	v_lshlrev_b32_e32 v114, 16, v112
	v_and_b32_e32 v115, 0xffff0000, v112
	v_lshlrev_b32_e32 v112, 16, v113
	v_and_b32_e32 v113, 0xffff0000, v113
	v_pk_mul_f32 v[112:113], v[102:103], v[112:113] op_sel_hi:[0,1]
	v_pk_mul_f32 v[128:129], v[92:93], v[128:129] op_sel_hi:[0,1]
	v_pk_mul_f32 v[114:115], v[102:103], v[114:115] op_sel_hi:[0,1]
	v_pk_fma_f32 v[6:7], v[118:119], v[112:113], v[6:7]
	v_lshlrev_b32_e32 v112, 16, v110
	v_and_b32_e32 v113, 0xffff0000, v110
	v_pk_fma_f32 v[12:13], v[116:117], v[128:129], v[12:13]
	v_pk_fma_f32 v[4:5], v[116:117], v[114:115], v[4:5]
	v_lshlrev_b32_e32 v114, 16, v111
	v_and_b32_e32 v115, 0xffff0000, v111
	v_pk_mul_f32 v[116:117], v[92:93], v[112:113] op_sel_hi:[0,1]
	global_load_dwordx4 v[110:113], v[108:109], off offset:3072
	v_pk_mul_f32 v[114:115], v[92:93], v[114:115] op_sel_hi:[0,1]
	v_mov_b32_e32 v118, v15
	s_waitcnt vmcnt(6)
	v_pk_fma_f32 v[22:23], v[122:123], v[114:115], v[22:23]
	v_lshlrev_b32_e32 v114, 16, v106
	v_and_b32_e32 v115, 0xffff0000, v106
	v_pk_fma_f32 v[20:21], v[120:121], v[116:117], v[20:21]
	v_lshlrev_b32_e32 v106, 16, v107
	v_and_b32_e32 v107, 0xffff0000, v107
	v_pk_mul_f32 v[114:115], v[102:103], v[114:115] op_sel_hi:[0,1]
	v_pk_mul_f32 v[106:107], v[102:103], v[106:107] op_sel_hi:[0,1]
	v_pk_fma_f32 v[16:17], v[120:121], v[114:115], v[16:17]
	v_mov_b32_e32 v114, v13
	v_mov_b32_e32 v115, v21
	v_pk_fma_f32 v[18:19], v[122:123], v[106:107], v[18:19]
	v_mov_b32_e32 v106, v12
	v_mov_b32_e32 v107, v20
	v_pk_mul_f32 v[114:115], v[114:115], v[114:115]
	v_add_co_u32_e32 v122, vcc, s30, v108
	v_pk_fma_f32 v[114:115], v[106:107], v[106:107], v[114:115]
	v_mov_b32_e32 v106, v14
	v_mov_b32_e32 v107, v22
	v_pk_mul_f32 v[116:117], v[106:107], v[106:107]
	v_addc_co_u32_e32 v123, vcc, 0, v109, vcc
	v_mov_b32_e32 v119, v23
	global_load_dwordx4 v[106:109], v[122:123], off
	v_pk_fma_f32 v[116:117], v[118:119], v[118:119], v[116:117]
	v_mov_b32_e32 v118, v7
	v_pk_add_f32 v[114:115], v[114:115], v[116:117]
	v_mov_b32_e32 v116, v5
	v_mov_b32_e32 v117, v17
	v_pk_add_f32 v[128:129], v[114:115], v[114:115] op_sel_hi:[0,1]
	v_mov_b32_e32 v114, v4
	v_mov_b32_e32 v115, v16
	v_pk_mul_f32 v[116:117], v[116:117], v[116:117]
	v_mov_b32_e32 v119, v19
	v_pk_fma_f32 v[114:115], v[114:115], v[114:115], v[116:117]
	v_mov_b32_e32 v116, v6
	v_mov_b32_e32 v117, v18
	v_pk_mul_f32 v[118:119], v[118:119], v[118:119]
	s_nop 0
	v_pk_fma_f32 v[116:117], v[116:117], v[116:117], v[118:119]
	s_nop 0
	v_pk_add_f32 v[114:115], v[114:115], v[116:117]
	s_nop 0
	v_pk_add_f32 v[130:131], v[114:115], v[114:115] op_sel_hi:[0,1]
	v_lshlrev_b32_e32 v114, 16, v104
	v_and_b32_e32 v115, 0xffff0000, v104
	v_lshlrev_b32_e32 v104, 16, v105
	v_and_b32_e32 v105, 0xffff0000, v105
	v_pk_mul_f32 v[114:115], v[92:93], v[114:115] op_sel_hi:[0,1]
	v_pk_mul_f32 v[104:105], v[92:93], v[104:105] op_sel_hi:[0,1]
	s_waitcnt vmcnt(2)
	v_pk_fma_f32 v[50:51], v[126:127], v[104:105], v[50:51]
	v_pk_fma_f32 v[48:49], v[124:125], v[114:115], v[48:49]
	v_lshlrev_b32_e32 v104, 16, v100
	v_and_b32_e32 v105, 0xffff0000, v100
	v_lshlrev_b32_e32 v100, 16, v101
	v_and_b32_e32 v101, 0xffff0000, v101
	global_load_dwordx4 v[114:117], v[122:123], off offset:1024
	v_pk_mul_f32 v[104:105], v[102:103], v[104:105] op_sel_hi:[0,1]
	v_pk_mul_f32 v[100:101], v[102:103], v[100:101] op_sel_hi:[0,1]
	v_pk_fma_f32 v[62:63], v[126:127], v[100:101], v[62:63]
	v_pk_fma_f32 v[60:61], v[124:125], v[104:105], v[60:61]
	v_pk_mul_f32 v[100:101], v[50:51], v[50:51]
	v_pk_mul_f32 v[104:105], v[48:49], v[48:49]
	s_nop 0
	v_pk_mov_b32 v[118:119], v[104:105], v[100:101] op_sel:[1,0]
	v_mov_b32_e32 v105, v101
	v_pk_add_f32 v[100:101], v[104:105], v[118:119]
	v_pk_mul_f32 v[104:105], v[62:63], v[62:63]
	v_pk_mul_f32 v[118:119], v[60:61], v[60:61]
	v_pk_add_f32 v[100:101], v[100:101], v[100:101] op_sel_hi:[0,1]
	v_pk_mov_b32 v[120:121], v[118:119], v[104:105] op_sel:[1,0]
	v_mov_b32_e32 v119, v105
	v_pk_add_f32 v[104:105], v[120:121], v[118:119]
	v_lshlrev_b32_e32 v118, 16, v66
	v_and_b32_e32 v119, 0xffff0000, v66
	v_pk_mul_f32 v[118:119], v[92:93], v[118:119] op_sel_hi:[0,1]
	v_lshlrev_b32_e32 v66, 16, v67
	v_and_b32_e32 v67, 0xffff0000, v67
	s_waitcnt vmcnt(2)
	v_pk_fma_f32 v[56:57], v[110:111], v[118:119], v[56:57]
	global_load_dwordx4 v[118:121], v[122:123], off offset:2048
	v_pk_mul_f32 v[66:67], v[92:93], v[66:67] op_sel_hi:[0,1]
	v_pk_fma_f32 v[58:59], v[112:113], v[66:67], v[58:59]
	v_lshlrev_b32_e32 v66, 16, v64
	v_and_b32_e32 v67, 0xffff0000, v64
	v_lshlrev_b32_e32 v64, 16, v65
	v_and_b32_e32 v65, 0xffff0000, v65
	v_pk_mul_f32 v[124:125], v[102:103], v[66:67] op_sel_hi:[0,1]
	v_pk_mul_f32 v[64:65], v[102:103], v[64:65] op_sel_hi:[0,1]
	v_pk_fma_f32 v[66:67], v[112:113], v[64:65], v[46:47]
	v_pk_fma_f32 v[64:65], v[110:111], v[124:125], v[44:45]
	global_load_dwordx4 v[110:113], v[122:123], off offset:3072
	v_mul_f32_e32 v44, v56, v56
	v_pk_fma_f32 v[124:125], v[56:57], v[56:57], v[44:45] op_sel_hi:[1,1,0]
	v_mul_f32_e32 v44, v58, v58
	v_pk_fma_f32 v[126:127], v[58:59], v[58:59], v[44:45] op_sel_hi:[1,1,0]
	v_mul_f32_e32 v44, v64, v64
	v_pk_fma_f32 v[132:133], v[64:65], v[64:65], v[44:45] op_sel_hi:[1,1,0]
	v_mul_f32_e32 v44, v66, v66
	v_pk_fma_f32 v[134:135], v[66:67], v[66:67], v[44:45] op_sel_hi:[1,1,0]
	v_lshlrev_b32_e32 v44, 16, v96
	v_and_b32_e32 v45, 0xffff0000, v96
	v_lshlrev_b32_e32 v46, 16, v97
	v_and_b32_e32 v47, 0xffff0000, v97
	v_pk_mul_f32 v[44:45], v[92:93], v[44:45] op_sel_hi:[0,1]
	v_pk_mul_f32 v[46:47], v[92:93], v[46:47] op_sel_hi:[0,1]
	s_waitcnt vmcnt(3)
; __device__ __forceinline__ f32x4 bf4(v2u u) { return (f32x4){bflo(u.x), bfhi(u.x), bflo(u.y), bfhi(u.y)}; }
; __device__ __forceinline__ void p5_row2(const Args& a, int rowA, int rowB, int lane) {
;     ...
; #pragma unroll
;     for (int jj = 0; jj < 8; ++jj) { const f32x4 gg = g1[64 * jj]; v[jj] = v[jj] + bf4(ma[jj]) * ra * gg; w[jj] = w[jj] + bf4(mb_[jj]) * rb * gg;
;         s += (v[jj].x * v[jj].x + v[jj].y * v[jj].y) + (v[jj].z * v[jj].z + v[jj].w * v[jj].w); t += (w[jj].x * w[jj].x + w[jj].y * w[jj].y) + (w[jj].z * w[jj].z + w[jj].w * w[jj].w); }
; #pragma unroll
;     for (int o = 1; o < 64; o <<= 1) { s += __shfl_xor(s, o); t += __shfl_xor(t, o); }
;     const float r0 = 1.f / sqrtf(s * (1.f / DMODEL) + RMS_EPS), r1 = 1.f / sqrtf(t * (1.f / DMODEL) + RMS_EPS);
	v_pk_fma_f32 v[46:47], v[108:109], v[46:47], v[54:55]
	v_pk_fma_f32 v[44:45], v[106:107], v[44:45], v[52:53]
	v_lshlrev_b32_e32 v52, 16, v98
	v_and_b32_e32 v53, 0xffff0000, v98
	v_lshlrev_b32_e32 v54, 16, v99
	v_and_b32_e32 v55, 0xffff0000, v99
	v_pk_mul_f32 v[52:53], v[102:103], v[52:53] op_sel_hi:[0,1]
	v_pk_mul_f32 v[54:55], v[102:103], v[54:55] op_sel_hi:[0,1]
	v_mul_f32_e32 v124, v44, v44
	v_mul_f32_e32 v126, v45, v45
	v_mul_f32_e32 v128, v46, v46
	v_mul_f32_e32 v100, v47, v47
	v_pk_add_f32 v[104:105], v[104:105], v[104:105] op_sel_hi:[0,1]
	v_pk_fma_f32 v[42:43], v[108:109], v[54:55], v[42:43]
	v_pk_fma_f32 v[40:41], v[106:107], v[52:53], v[40:41]
	v_pk_add_f32 v[52:53], v[124:125], v[126:127]
	v_pk_add_f32 v[54:55], v[100:101], v[128:129]
	v_mul_f32_e32 v132, v40, v40
	v_pk_add_f32 v[52:53], v[52:53], v[54:55]
	v_mul_f32_e32 v134, v41, v41
	v_mul_f32_e32 v104, v42, v42
	v_mul_f32_e32 v130, v43, v43
	v_pk_add_f32 v[96:97], v[52:53], v[52:53] op_sel_hi:[0,1]
	v_pk_add_f32 v[52:53], v[132:133], v[134:135]
	v_pk_add_f32 v[54:55], v[104:105], v[130:131]
	v_lshlrev_b32_e32 v100, 16, v82
	v_pk_add_f32 v[52:53], v[52:53], v[54:55]
	v_lshlrev_b32_e32 v54, 16, v89
	v_pk_add_f32 v[98:99], v[52:53], v[52:53] op_sel_hi:[0,1]
	v_lshlrev_b32_e32 v52, 16, v88
	v_and_b32_e32 v53, 0xffff0000, v88
	v_and_b32_e32 v55, 0xffff0000, v89
	v_pk_mul_f32 v[52:53], v[92:93], v[52:53] op_sel_hi:[0,1]
	v_pk_mul_f32 v[54:55], v[92:93], v[54:55] op_sel_hi:[0,1]
	s_waitcnt vmcnt(2)
	v_pk_fma_f32 v[54:55], v[116:117], v[54:55], v[34:35]
	v_pk_fma_f32 v[52:53], v[114:115], v[52:53], v[32:33]
	v_lshlrev_b32_e32 v32, 16, v94
	v_and_b32_e32 v33, 0xffff0000, v94
	v_lshlrev_b32_e32 v34, 16, v95
	v_and_b32_e32 v35, 0xffff0000, v95
	v_pk_mul_f32 v[32:33], v[102:103], v[32:33] op_sel_hi:[0,1]
	v_pk_mul_f32 v[34:35], v[102:103], v[34:35] op_sel_hi:[0,1]
	v_pk_fma_f32 v[34:35], v[116:117], v[34:35], v[38:39]
	v_pk_fma_f32 v[32:33], v[114:115], v[32:33], v[36:37]
	v_pk_mul_f32 v[36:37], v[54:55], v[54:55]
	v_pk_mul_f32 v[38:39], v[52:53], v[52:53]
	v_and_b32_e32 v101, 0xffff0000, v82
	v_pk_mov_b32 v[88:89], v[38:39], v[36:37] op_sel:[1,0]
	v_mov_b32_e32 v39, v37
	v_pk_add_f32 v[36:37], v[38:39], v[88:89]
	v_pk_mul_f32 v[38:39], v[34:35], v[34:35]
	v_pk_mul_f32 v[88:89], v[32:33], v[32:33]
	v_pk_add_f32 v[36:37], v[36:37], v[36:37] op_sel_hi:[0,1]
	v_pk_mov_b32 v[94:95], v[88:89], v[38:39] op_sel:[1,0]
	v_mov_b32_e32 v89, v39
	v_pk_add_f32 v[38:39], v[94:95], v[88:89]
	v_lshlrev_b32_e32 v88, 16, v84
	v_and_b32_e32 v89, 0xffff0000, v84
	v_lshlrev_b32_e32 v84, 16, v85
	v_and_b32_e32 v85, 0xffff0000, v85
	v_pk_mul_f32 v[88:89], v[92:93], v[88:89] op_sel_hi:[0,1]
	v_pk_mul_f32 v[84:85], v[92:93], v[84:85] op_sel_hi:[0,1]
	s_waitcnt vmcnt(1)
	v_pk_fma_f32 v[26:27], v[120:121], v[84:85], v[26:27]
	v_pk_fma_f32 v[24:25], v[118:119], v[88:89], v[24:25]
	v_lshlrev_b32_e32 v84, 16, v90
	v_and_b32_e32 v85, 0xffff0000, v90
	v_lshlrev_b32_e32 v88, 16, v91
	v_and_b32_e32 v89, 0xffff0000, v91
	v_pk_mul_f32 v[84:85], v[102:103], v[84:85] op_sel_hi:[0,1]
	v_mul_f32_e32 v36, v24, v24
	v_pk_mul_f32 v[88:89], v[102:103], v[88:89] op_sel_hi:[0,1]
	v_pk_fma_f32 v[28:29], v[118:119], v[84:85], v[28:29]
	v_pk_fma_f32 v[84:85], v[24:25], v[24:25], v[36:37] op_sel_hi:[1,1,0]
	v_mul_f32_e32 v36, v26, v26
	v_lshlrev_b32_e32 v82, 16, v83
	v_and_b32_e32 v83, 0xffff0000, v83
	v_pk_fma_f32 v[30:31], v[120:121], v[88:89], v[30:31]
	v_pk_fma_f32 v[88:89], v[26:27], v[26:27], v[36:37] op_sel_hi:[1,1,0]
	v_mul_f32_e32 v36, v28, v28
	v_pk_mul_f32 v[100:101], v[92:93], v[100:101] op_sel_hi:[0,1]
	v_pk_mul_f32 v[82:83], v[92:93], v[82:83] op_sel_hi:[0,1]
	v_pk_fma_f32 v[90:91], v[28:29], v[28:29], v[36:37] op_sel_hi:[1,1,0]
	v_mul_f32_e32 v36, v30, v30
	s_waitcnt vmcnt(0)
	v_pk_fma_f32 v[10:11], v[82:83], v[112:113], v[10:11]
	v_pk_fma_f32 v[8:9], v[100:101], v[110:111], v[8:9]
	v_lshlrev_b32_e32 v82, 16, v86
	v_and_b32_e32 v83, 0xffff0000, v86
	v_pk_fma_f32 v[94:95], v[30:31], v[30:31], v[36:37] op_sel_hi:[1,1,0]
	v_pk_mul_f32 v[82:83], v[102:103], v[82:83] op_sel_hi:[0,1]
	v_mul_f32_e32 v84, v8, v8
	v_mul_f32_e32 v88, v9, v9
	v_mul_f32_e32 v96, v10, v10
	v_mul_f32_e32 v36, v11, v11
	v_pk_fma_f32 v[0:1], v[110:111], v[82:83], v[0:1]
	v_pk_add_f32 v[82:83], v[84:85], v[88:89]
	v_pk_add_f32 v[36:37], v[36:37], v[96:97]
	v_lshlrev_b32_e32 v86, 16, v87
	v_pk_add_f32 v[36:37], v[82:83], v[36:37]
	v_and_b32_e32 v87, 0xffff0000, v87
	v_add_f32_e32 v82, v36, v37
	ds_bpermute_b32 v83, v200, v82
	v_pk_mul_f32 v[86:87], v[102:103], v[86:87] op_sel_hi:[0,1]
	v_lshl_add_u64 v[84:85], s[74:75], 0, v[80:81]
	v_pk_fma_f32 v[2:3], v[112:113], v[86:87], v[2:3]
	global_load_dwordx4 v[86:89], v[84:85], off
	s_waitcnt lgkmcnt(0)
	v_add_f32_e32 v82, v82, v83
	ds_bpermute_b32 v83, v201, v82
	v_pk_add_f32 v[38:39], v[38:39], v[38:39] op_sel_hi:[0,1]
	v_mul_f32_e32 v90, v0, v0
	v_mul_f32_e32 v94, v1, v1
	v_mul_f32_e32 v38, v2, v2
	v_mul_f32_e32 v98, v3, v3
	v_pk_add_f32 v[36:37], v[90:91], v[94:95]
	v_pk_add_f32 v[38:39], v[38:39], v[98:99]
	s_nop 0
	v_pk_add_f32 v[36:37], v[36:37], v[38:39]
	s_waitcnt lgkmcnt(0)
	v_add_f32_e32 v38, v82, v83
	ds_bpermute_b32 v39, v202, v38
	v_add_f32_e32 v36, v36, v37
	ds_bpermute_b32 v37, v200, v36
	s_waitcnt lgkmcnt(1)
	v_add_f32_e32 v38, v38, v39
	ds_bpermute_b32 v39, v203, v38
	s_waitcnt lgkmcnt(1)
	v_add_f32_e32 v36, v36, v37
	ds_bpermute_b32 v37, v201, v36
	s_waitcnt lgkmcnt(1)
	v_add_f32_e32 v38, v38, v39
	ds_bpermute_b32 v39, v204, v38
	s_waitcnt lgkmcnt(1)
	v_add_f32_e32 v36, v36, v37
	ds_bpermute_b32 v37, v202, v36
	s_waitcnt lgkmcnt(1)
	v_add_f32_e32 v38, v38, v39
	ds_bpermute_b32 v39, v205, v38
	s_waitcnt lgkmcnt(1)
; __device__ __forceinline__ v2u pk4(f32x4 v) { v2u o; o.x = pk2(v.x, v.y); o.y = pk2(v.z, v.w); return o; }
; __device__ __forceinline__ void p5_row2(const Args& a, int rowA, int rowB, int lane) {
;     ...
;     for (int o = 1; o < 64; o <<= 1) { s += __shfl_xor(s, o); t += __shfl_xor(t, o); }
;     const float r0 = 1.f / sqrtf(s * (1.f / DMODEL) + RMS_EPS), r1 = 1.f / sqrtf(t * (1.f / DMODEL) + RMS_EPS);
;     f32x4* oA = (f32x4*)(a.out + (size_t)rowA * 2048) + lane; f32x4* oB = (f32x4*)(a.out + (size_t)rowB * 2048) + lane;
;     v2u* nA = (v2u*)((bf16*)(a.ws + WS_XN) + (size_t)rowA * 2048) + lane; v2u* nB = (v2u*)((bf16*)(a.ws + WS_XN) + (size_t)rowB * 2048) + lane;
; #pragma unroll
;     for (int jj = 0; jj < 8; ++jj) { const f32x4 gg = g2[64 * jj]; oA[64 * jj] = v[jj]; oB[64 * jj] = w[jj]; nA[64 * jj] = pk4(v[jj] * r0 * gg); nB[64 * jj] = pk4(w[jj] * r1 * gg); }
	v_add_f32_e32 v36, v36, v37
	ds_bpermute_b32 v37, v203, v36
	s_waitcnt lgkmcnt(1)
	v_add_f32_e32 v38, v38, v39
	v_fmamk_f32 v38, v38, 0x3a000000, v93
	v_mul_f32_e32 v39, 0x4f800000, v38
	v_cmp_gt_f32_e32 vcc, s31, v38
	s_waitcnt lgkmcnt(0)
	v_add_f32_e32 v36, v36, v37
	ds_bpermute_b32 v37, v204, v36
	v_cndmask_b32_e32 v38, v38, v39, vcc
	v_sqrt_f32_e32 v39, v38
	s_waitcnt lgkmcnt(0)
	v_add_f32_e32 v36, v36, v37
	v_add_u32_e32 v82, -1, v39
	v_fma_f32 v83, -v82, v39, v38
	v_cmp_ge_f32_e64 s[4:5], 0, v83
	v_add_u32_e32 v83, 1, v39
	ds_bpermute_b32 v37, v205, v36
	v_cndmask_b32_e64 v82, v39, v82, s[4:5]
	v_fma_f32 v39, -v83, v39, v38
	v_cmp_lt_f32_e64 s[4:5], 0, v39
	s_waitcnt lgkmcnt(0)
	v_add_f32_e32 v36, v36, v37
	v_cndmask_b32_e64 v39, v82, v83, s[4:5]
	v_mul_f32_e32 v82, 0x37800000, v39
	v_cndmask_b32_e32 v39, v39, v82, vcc
	v_cmp_class_f32_e32 vcc, v38, v103
	v_fmamk_f32 v36, v36, 0x3a000000, v93
	v_mul_f32_e32 v90, 0x4f800000, v36
	v_cndmask_b32_e32 v38, v39, v38, vcc
	v_div_scale_f32 v39, s[2:3], v38, v38, 1.0
	v_rcp_f32_e32 v82, v39
	v_cmp_gt_f32_e64 s[4:5], s31, v36
	v_fma_f32 v37, -v39, v82, 1.0
	s_nop 0
	v_cndmask_b32_e64 v36, v36, v90, s[4:5]
	v_fmac_f32_e32 v82, v37, v82
	v_div_scale_f32 v37, vcc, 1.0, v38, 1.0
	v_sqrt_f32_e32 v90, v36
	v_mul_f32_e32 v83, v37, v82
	v_fma_f32 v91, -v39, v83, v37
	v_fmac_f32_e32 v83, v91, v82
	v_fma_f32 v37, -v39, v83, v37
	v_add_u32_e32 v39, -1, v90
	v_fma_f32 v91, -v39, v90, v36
	v_cmp_ge_f32_e64 s[8:9], 0, v91
	v_add_u32_e32 v91, 1, v90
	s_nop 0
	v_cndmask_b32_e64 v39, v90, v39, s[8:9]
	v_fma_f32 v90, -v91, v90, v36
	v_cmp_lt_f32_e64 s[8:9], 0, v90
	s_nop 1
	v_cndmask_b32_e64 v39, v39, v91, s[8:9]
	v_mul_f32_e32 v90, 0x37800000, v39
	v_cndmask_b32_e64 v39, v39, v90, s[4:5]
	v_cmp_class_f32_e64 s[4:5], v36, v103
	s_nop 1
	v_cndmask_b32_e64 v39, v39, v36, s[4:5]
	v_div_scale_f32 v90, s[2:3], v39, v39, 1.0
	v_rcp_f32_e32 v91, v90
	v_div_fmas_f32 v36, v37, v82, v83
	v_div_fixup_f32 v36, v36, v38, 1.0
	s_add_u32 s2, s22, s16
	v_fma_f32 v37, -v90, v91, 1.0
	v_fmac_f32_e32 v91, v37, v91
	v_div_scale_f32 v37, vcc, 1.0, v39, 1.0
	v_mul_f32_e32 v38, v37, v91
	v_fma_f32 v82, -v90, v38, v37
	v_fmac_f32_e32 v38, v82, v91
	v_fma_f32 v37, -v90, v38, v37
	s_addc_u32 s3, s23, s17
	v_div_fmas_f32 v37, v37, v91, v38
	v_lshl_add_u64 v[90:91], s[2:3], 0, v[80:81]
	s_add_u32 s2, s88, s28
	s_addc_u32 s3, s89, s29
	v_div_fixup_f32 v82, v37, v39, 1.0
	v_lshl_add_u64 v[80:81], s[2:3], 0, v[80:81]
	s_add_u32 s2, s60, s26
	global_store_dwordx4 v[90:91], v[12:15], off nt
	global_store_dwordx4 v[80:81], v[4:7], off nt
	s_addc_u32 s3, s61, s27
	v_pk_mul_f32 v[12:13], v[12:13], v[36:37] op_sel_hi:[1,0]
	v_pk_mul_f32 v[14:15], v[14:15], v[36:37] op_sel_hi:[1,0]
	s_waitcnt vmcnt(2)
	v_pk_mul_f32 v[12:13], v[86:87], v[12:13]
	v_pk_mul_f32 v[4:5], v[4:5], v[82:83] op_sel_hi:[1,0]
	v_pk_mul_f32 v[6:7], v[6:7], v[82:83] op_sel_hi:[1,0]
	v_lshl_add_u64 v[38:39], s[2:3], 0, v[78:79]
	v_pk_mul_f32 v[14:15], v[88:89], v[14:15]
	v_cvt_pk_bf16_f32 v78, v12, v13
	v_add_co_u32_e32 v12, vcc, s33, v76
	v_pk_mul_f32 v[6:7], v[88:89], v[6:7]
	v_pk_mul_f32 v[4:5], v[86:87], v[4:5]
	v_cvt_pk_bf16_f32 v79, v14, v15
	v_addc_co_u32_e32 v13, vcc, 0, v77, vcc
	v_cvt_pk_bf16_f32 v4, v4, v5
	v_cvt_pk_bf16_f32 v5, v6, v7
	global_store_dwordx2 v[12:13], v[78:79], off
	global_store_dwordx2 v[38:39], v[4:5], off
	global_load_dwordx4 v[4:7], v[84:85], off offset:1024
	s_nop 0
	global_store_dwordx4 v[90:91], v[20:23], off offset:1024 nt
	global_store_dwordx4 v[80:81], v[16:19], off offset:1024 nt
	v_pk_mul_f32 v[14:15], v[20:21], v[36:37] op_sel_hi:[1,0]
	v_pk_mul_f32 v[20:21], v[22:23], v[36:37] op_sel_hi:[1,0]
	v_pk_mul_f32 v[22:23], v[46:47], v[36:37] op_sel_hi:[1,0]
	s_add_i32 s64, s64, s10
	s_add_u32 s12, s12, s14
	s_addc_u32 s13, s13, s15
	s_add_u32 s24, s24, s18
	s_addc_u32 s25, s25, s19
	s_add_u32 s22, s22, s18
	s_addc_u32 s23, s23, s19
	s_cmpk_gt_i32 s64, 0x3fff
	s_waitcnt vmcnt(2)
	v_pk_mul_f32 v[20:21], v[6:7], v[20:21]
	v_pk_mul_f32 v[14:15], v[4:5], v[14:15]
	s_nop 0
	v_cvt_pk_bf16_f32 v14, v14, v15
	v_cvt_pk_bf16_f32 v15, v20, v21
	global_store_dwordx2 v[12:13], v[14:15], off offset:512
	v_pk_mul_f32 v[14:15], v[16:17], v[82:83] op_sel_hi:[1,0]
	v_pk_mul_f32 v[16:17], v[18:19], v[82:83] op_sel_hi:[1,0]
	v_pk_mul_f32 v[4:5], v[4:5], v[14:15]
	v_pk_mul_f32 v[6:7], v[6:7], v[16:17]
	v_cvt_pk_bf16_f32 v4, v4, v5
	v_cvt_pk_bf16_f32 v5, v6, v7
	global_store_dwordx2 v[38:39], v[4:5], off offset:512
	global_load_dwordx4 v[4:7], v[84:85], off offset:2048
	v_pk_mul_f32 v[14:15], v[48:49], v[36:37] op_sel_hi:[1,0]
	v_pk_mul_f32 v[16:17], v[50:51], v[36:37] op_sel_hi:[1,0]
	global_store_dwordx4 v[90:91], v[48:51], off offset:2048 nt
	global_store_dwordx4 v[80:81], v[60:63], off offset:2048 nt
	v_pk_mul_f32 v[20:21], v[44:45], v[36:37] op_sel_hi:[1,0]
	s_waitcnt vmcnt(2)
; __device__ __forceinline__ v2u pk4(f32x4 v) { v2u o; o.x = pk2(v.x, v.y); o.y = pk2(v.z, v.w); return o; }
; __device__ __forceinline__ void p5_row2(const Args& a, int rowA, int rowB, int lane) {
;     ...
;     f32x4* oA = (f32x4*)(a.out + (size_t)rowA * 2048) + lane; f32x4* oB = (f32x4*)(a.out + (size_t)rowB * 2048) + lane;
;     v2u* nA = (v2u*)((bf16*)(a.ws + WS_XN) + (size_t)rowA * 2048) + lane; v2u* nB = (v2u*)((bf16*)(a.ws + WS_XN) + (size_t)rowB * 2048) + lane;
; #pragma unroll
;     for (int jj = 0; jj < 8; ++jj) { const f32x4 gg = g2[64 * jj]; oA[64 * jj] = v[jj]; oB[64 * jj] = w[jj]; nA[64 * jj] = pk4(v[jj] * r0 * gg); nB[64 * jj] = pk4(w[jj] * r1 * gg); }
	v_pk_mul_f32 v[16:17], v[6:7], v[16:17]
	v_pk_mul_f32 v[14:15], v[4:5], v[14:15]
	s_nop 0
	v_cvt_pk_bf16_f32 v14, v14, v15
	v_cvt_pk_bf16_f32 v15, v16, v17
	global_store_dwordx2 v[12:13], v[14:15], off offset:1024
	v_pk_mul_f32 v[14:15], v[60:61], v[82:83] op_sel_hi:[1,0]
	v_pk_mul_f32 v[16:17], v[62:63], v[82:83] op_sel_hi:[1,0]
	v_pk_mul_f32 v[4:5], v[4:5], v[14:15]
	v_pk_mul_f32 v[6:7], v[6:7], v[16:17]
	v_cvt_pk_bf16_f32 v4, v4, v5
	v_cvt_pk_bf16_f32 v5, v6, v7
	global_store_dwordx2 v[38:39], v[4:5], off offset:1024
	global_load_dwordx4 v[4:7], v[84:85], off offset:3072
	v_pk_mul_f32 v[14:15], v[56:57], v[36:37] op_sel_hi:[1,0]
	v_pk_mul_f32 v[16:17], v[58:59], v[36:37] op_sel_hi:[1,0]
	global_store_dwordx4 v[90:91], v[56:59], off offset:3072 nt
	global_store_dwordx4 v[80:81], v[64:67], off offset:3072 nt
	s_waitcnt vmcnt(2)
	v_pk_mul_f32 v[16:17], v[16:17], v[6:7]
	v_pk_mul_f32 v[14:15], v[14:15], v[4:5]
	s_nop 0
	v_cvt_pk_bf16_f32 v14, v14, v15
	v_cvt_pk_bf16_f32 v15, v16, v17
	global_store_dwordx2 v[12:13], v[14:15], off offset:1536
	v_pk_mul_f32 v[14:15], v[64:65], v[82:83] op_sel_hi:[1,0]
	v_pk_mul_f32 v[16:17], v[66:67], v[82:83] op_sel_hi:[1,0]
	v_pk_mul_f32 v[4:5], v[14:15], v[4:5]
	v_pk_mul_f32 v[6:7], v[16:17], v[6:7]
	v_cvt_pk_bf16_f32 v4, v4, v5
	v_cvt_pk_bf16_f32 v5, v6, v7
	v_add_co_u32_e32 v14, vcc, s30, v84
	global_store_dwordx2 v[38:39], v[4:5], off offset:1536
	s_nop 0
	v_addc_co_u32_e32 v15, vcc, 0, v85, vcc
	global_load_dwordx4 v[4:7], v[14:15], off
	v_add_co_u32_e32 v16, vcc, s30, v90
	s_waitcnt vmcnt(0)
	v_pk_mul_f32 v[22:23], v[22:23], v[6:7]
	v_addc_co_u32_e32 v17, vcc, 0, v91, vcc
	v_add_co_u32_e32 v18, vcc, s30, v80
	v_pk_mul_f32 v[20:21], v[20:21], v[4:5]
	s_nop 0
	v_addc_co_u32_e32 v19, vcc, 0, v81, vcc
	v_cvt_pk_bf16_f32 v20, v20, v21
	v_cvt_pk_bf16_f32 v21, v22, v23
	global_store_dwordx4 v[16:17], v[44:47], off nt
	global_store_dwordx4 v[18:19], v[40:43], off nt
	global_store_dwordx2 v[12:13], v[20:21], off offset:2048
	v_pk_mul_f32 v[20:21], v[40:41], v[82:83] op_sel_hi:[1,0]
	v_pk_mul_f32 v[22:23], v[42:43], v[82:83] op_sel_hi:[1,0]
	v_pk_mul_f32 v[4:5], v[20:21], v[4:5]
	v_pk_mul_f32 v[6:7], v[22:23], v[6:7]
	v_cvt_pk_bf16_f32 v4, v4, v5
	v_cvt_pk_bf16_f32 v5, v6, v7
	global_store_dwordx2 v[38:39], v[4:5], off offset:2048
	global_load_dwordx4 v[4:7], v[14:15], off offset:1024
	v_pk_mul_f32 v[20:21], v[52:53], v[36:37] op_sel_hi:[1,0]
	v_pk_mul_f32 v[22:23], v[54:55], v[36:37] op_sel_hi:[1,0]
	global_store_dwordx4 v[16:17], v[52:55], off offset:1024 nt
	global_store_dwordx4 v[18:19], v[32:35], off offset:1024 nt
	s_waitcnt vmcnt(2)
	v_pk_mul_f32 v[22:23], v[22:23], v[6:7]
	v_pk_mul_f32 v[20:21], v[20:21], v[4:5]
	s_nop 0
	v_cvt_pk_bf16_f32 v20, v20, v21
	v_cvt_pk_bf16_f32 v21, v22, v23
	global_store_dwordx2 v[12:13], v[20:21], off offset:2560
	v_pk_mul_f32 v[20:21], v[32:33], v[82:83] op_sel_hi:[1,0]
	v_pk_mul_f32 v[22:23], v[34:35], v[82:83] op_sel_hi:[1,0]
	v_pk_mul_f32 v[4:5], v[20:21], v[4:5]
	v_pk_mul_f32 v[6:7], v[22:23], v[6:7]
	v_cvt_pk_bf16_f32 v4, v4, v5
	v_cvt_pk_bf16_f32 v5, v6, v7
	global_store_dwordx2 v[38:39], v[4:5], off offset:2560
	global_load_dwordx4 v[4:7], v[14:15], off offset:2048
	v_pk_mul_f32 v[20:21], v[24:25], v[36:37] op_sel_hi:[1,0]
	v_pk_mul_f32 v[22:23], v[26:27], v[36:37] op_sel_hi:[1,0]
	v_pk_mul_f32 v[32:33], v[28:29], v[82:83] op_sel_hi:[1,0]
	v_pk_mul_f32 v[34:35], v[30:31], v[82:83] op_sel_hi:[1,0]
	global_store_dwordx4 v[16:17], v[24:27], off offset:2048 nt
	global_store_dwordx4 v[18:19], v[28:31], off offset:2048 nt
	s_waitcnt vmcnt(2)
	v_pk_mul_f32 v[22:23], v[22:23], v[6:7]
	v_pk_mul_f32 v[20:21], v[20:21], v[4:5]
	v_pk_mul_f32 v[6:7], v[34:35], v[6:7]
	v_pk_mul_f32 v[4:5], v[32:33], v[4:5]
	v_cvt_pk_bf16_f32 v20, v20, v21
	v_cvt_pk_bf16_f32 v21, v22, v23
	v_cvt_pk_bf16_f32 v4, v4, v5
	v_cvt_pk_bf16_f32 v5, v6, v7
	global_store_dwordx2 v[12:13], v[20:21], off offset:3072
	global_store_dwordx2 v[38:39], v[4:5], off offset:3072
	global_load_dwordx4 v[4:7], v[14:15], off offset:3072
	v_pk_mul_f32 v[14:15], v[8:9], v[36:37] op_sel_hi:[1,0]
	v_pk_mul_f32 v[20:21], v[10:11], v[36:37] op_sel_hi:[1,0]
	v_pk_mul_f32 v[22:23], v[0:1], v[82:83] op_sel_hi:[1,0]
	v_pk_mul_f32 v[24:25], v[2:3], v[82:83] op_sel_hi:[1,0]
	global_store_dwordx4 v[16:17], v[8:11], off offset:3072 nt
	global_store_dwordx4 v[18:19], v[0:3], off offset:3072 nt
	s_waitcnt vmcnt(2)
	s_nop 0
	v_pk_mul_f32 v[0:1], v[20:21], v[6:7]
	v_pk_mul_f32 v[2:3], v[14:15], v[4:5]
	v_pk_mul_f32 v[6:7], v[24:25], v[6:7]
	v_pk_mul_f32 v[4:5], v[22:23], v[4:5]
	v_cvt_pk_bf16_f32 v2, v2, v3
	v_cvt_pk_bf16_f32 v3, v0, v1
	v_cvt_pk_bf16_f32 v0, v4, v5
	v_cvt_pk_bf16_f32 v1, v6, v7
	global_store_dwordx2 v[12:13], v[2:3], off offset:3584
	global_store_dwordx2 v[38:39], v[0:1], off offset:3584
	s_cbranch_scc1 .LBB0_795
